# NSA selected loop: two key-tile pairs per barrier interval (32 KB double-buffered LDS stage), halves the workgroup barriers and lets the waves drift inside an interval
# baseline (speedup 1.0000x reference)
; #define TIDX get_tid_()
; DI float bf2f(bf16_t b) { return __uint_as_float(((unsigned)b) << 16); }
; DI int crow(int i, int h) { return (i & 3) + 8 * (i >> 2) + 4 * h; }
; DI void nsa_main_item(const Params& p, int b, int head, int qb, const unsigned char* blut, const float* tbl) {
;   const int lane = TIDX & 63, r = lane & 31, h = lane >> 5;
;   const int g = head / 3, bg = b * 2 + g;
;   const int t = qb * 32 + r;
;   const float* tblh = tbl + head * 32;
;   bf16x8 qf[4];
;   load_q(qf, (const bf16_t*)(p.ws + OFF_QN) + (size_t)(b * 4096 + t) * 384 + head * 64 + 8 * h);
;   const unsigned long long selm = ((const unsigned long long*)(p.ws + OFF_SELM))[(size_t)bg * 4096 + t];
;   const float* gates = (const float*)(p.ws + OFF_GATES) + (size_t)(b * 4096 + t) * 18 + head * 3;
;   const float g1 = gates[1];
;   f32x16 y0, y1;
;   {
;     const bf16_t* oc = (const bf16_t*)(p.ws + OFF_OC) + (size_t)(b * 4096 + t) * 384 + head * 64;
;     const bf16_t* yw = (const bf16_t*)(p.ws + OFF_Y) + (size_t)(b * 4096 + t) * 768 + head * 64;
; #pragma unroll
;     for (int i = 0; i < 16; ++i) { y0[i] = bf2f(oc[crow(i, h)]) + bf2f(yw[crow(i, h)]); y1[i] = bf2f(oc[32 + crow(i, h)]) + bf2f(yw[32 + crow(i, h)]); }
;   }
;     ...
;   for (;;) {
;     const int item = wave_fetch(ctr);
;     if (item >= 128 * 48) break;
;     const int qb = 127 - item / 48, sub = item % 48;
;     nsa_main_item(p, sub / 6, sub % 6, qb, blut, tbl);
.LfY_skip:
	s_or_b64 exec, exec, s[8:9]
	s_barrier
	ds_read_b32 v0, v0
	v_lshrrev_b32_e32 v1, 6, v129
	s_waitcnt lgkmcnt(0)
	v_add_u32_e32 v0, v0, v1
	s_movk_i32 s8, 0x300
	s_waitcnt lgkmcnt(0)
	v_cmp_gt_i32_e32 vcc, s8, v0
	s_mov_b64 s[8:9], -1
	s_and_saveexec_b64 s[14:15], vcc
	s_cbranch_execz .LBB0_702
	v_lshrrev_b32_e32 v1, 4, v0
	v_lshlrev_b32_e32 v1, 3, v1
	v_and_b32_e32 v2, 7, v0
	v_add_u32_e32 v1, v1, v2
	v_bfe_u32 v2, v0, 3, 1
	v_mul_u32_u24_e32 v2, 3, v2
	v_add_u32_e32 v2, v2, v1
	v_mul_u32_u24_e32 v0, 0x5556, v1
	v_lshrrev_b32_e32 v0, 16, v0
	v_mul_u32_u24_e32 v0, 45, v0
	v_add3_u32 v0, v0, v2, s101
	s_mov_b32 s8, 0xd5555555
	v_mul_hi_i32 v1, v0, s8
	v_lshrrev_b32_e32 v2, 31, v1
	v_ashrrev_i32_e32 v1, 3, v1
	s_movk_i32 s8, 0x7f
	v_add3_u32 v217, v1, v2, s8
	s_mov_b32 s8, 0x2aaaaaab
	v_mul_hi_i32 v1, v0, s8
	v_lshrrev_b32_e32 v2, 31, v1
	v_lshrrev_b32_e32 v1, 3, v1
	v_add_u32_e32 v1, v1, v2
	v_mul_lo_u32 v1, v1, 48
	v_sub_u32_e32 v0, v0, v1
	v_mul_lo_u16_e32 v1, 43, v0
	v_lshrrev_b16_e32 v2, 15, v1
	v_add_u16_sdwa v1, v1, v2 dst_sel:DWORD dst_unused:UNUSED_PAD src0_sel:BYTE_1 src1_sel:DWORD
	v_bfe_i32 v2, v1, 0, 8
	v_mul_lo_u16_e32 v1, 6, v1
	v_sub_u16_e32 v0, v0, v1
	v_bfe_i32 v28, v0, 0, 8
	v_mov_b32_e32 v0, v129
	v_lshlrev_b32_e32 v31, 5, v217
	v_and_b32_e32 v29, 31, v0
	v_bfe_u32 v30, v0, 5, 1
	v_mul_lo_u16_e32 v0, 0x56, v28
	v_lshrrev_b16_e32 v1, 15, v0
	v_add_u16_sdwa v0, v0, v1 dst_sel:DWORD dst_unused:UNUSED_PAD src0_sel:BYTE_1 src1_sel:DWORD
	v_readlane_b32 s8, v253, 13
	v_bfe_i32 v0, v0, 0, 8
	v_or_b32_e32 v10, v29, v31
	v_readlane_b32 s9, v253, 14
	v_lshl_add_u32 v8, v2, 1, v0
	v_lshl_add_u32 v22, v2, 12, v10
	v_mov_b64_e32 v[0:1], s[8:9]
	s_movk_i32 s23, 0x300
	v_mad_i64_i32 v[0:1], s[8:9], v22, s23, v[0:1]
	v_lshlrev_b32_e32 v2, 6, v28
	v_ashrrev_i32_e32 v3, 31, v2
	v_readlane_b32 s8, v253, 23
	v_lshlrev_b64 v[2:3], 1, v[2:3]
	v_readlane_b32 s9, v253, 24
	v_lshl_add_u64 v[4:5], v[0:1], 0, v[2:3]
	v_lshlrev_b32_e32 v130, 3, v30
	v_mov_b64_e32 v[0:1], s[8:9]
	v_mad_i64_i32 v[0:1], s[8:9], v22, s23, v[0:1]
	v_readlane_b32 s8, v253, 19
	v_readlane_b32 s9, v253, 20
	v_lshl_add_u64 v[0:1], v[0:1], 0, v[2:3]
	v_ashrrev_i32_e32 v9, 31, v8
	v_mov_b64_e32 v[6:7], s[8:9]
	s_movk_i32 s8, 0x600
	v_mad_i64_i32 v[6:7], s[8:9], v22, s8, v[6:7]
	v_lshl_add_u64 v[2:3], v[6:7], 0, v[2:3]
	v_lshl_add_u64 v[12:13], v[0:1], 0, v[130:131]
	v_readlane_b32 s8, v253, 25
	v_lshlrev_b32_e32 v0, 3, v29
	v_lshl_add_u64 v[132:133], v[2:3], 0, v[130:131]
	v_lshlrev_b64 v[14:15], 19, v[8:9]
	v_readlane_b32 s9, v253, 26
	v_lshl_or_b32 v130, v30, 8, v0
	v_lshlrev_b32_e32 v20, 1, v130
	v_lshl_add_u64 v[16:17], s[8:9], 0, v[14:15]
	v_mov_b32_e32 v21, v131
	v_lshl_add_u64 v[148:149], v[16:17], 0, v[20:21]
	global_load_dwordx4 v[0:3], v[148:149], off
	v_lshlrev_b32_e32 v6, 4, v30
	v_mov_b32_e32 v7, v131
	v_lshl_add_u64 v[4:5], v[4:5], 0, v[6:7]
	global_load_dwordx4 v[80:83], v[4:5], off
	v_mov_b64_e32 v[6:7], s[34:35]
	s_movk_i32 s8, 0x48
	v_mad_i64_i32 v[6:7], s[8:9], v22, s8, v[6:7]
	v_mul_i32_i24_e32 v22, 3, v28
	v_ashrrev_i32_e32 v23, 31, v22
	v_cmp_eq_u32_e32 vcc, 0, v217
	v_lshl_add_u64 v[6:7], v[22:23], 2, v[6:7]
	s_mov_b32 s8, 0x165c4000
	v_cndmask_b32_e64 v18, v197, 0, vcc
	v_add_co_u32_e32 v22, vcc, s8, v6
	v_readlane_b32 s8, v253, 21
	s_nop 0
	v_addc_co_u32_e32 v23, vcc, 0, v7, vcc
	global_load_dwordx4 v[84:87], v[4:5], off offset:32
	global_load_dwordx4 v[88:91], v[4:5], off offset:64
	global_load_dwordx4 v[92:95], v[4:5], off offset:96
	global_load_dwordx2 v[136:137], v[12:13], off offset:64
	global_load_dwordx2 v[144:145], v[12:13], off offset:80
	global_load_dwordx2 v[150:151], v[12:13], off offset:32
	global_load_dwordx2 v[160:161], v[12:13], off offset:48
	global_load_dwordx2 v[134:135], v[132:133], off
	global_load_dwordx2 v[142:143], v[132:133], off offset:16
	global_load_dwordx2 v[152:153], v[132:133], off offset:32
	global_load_dwordx2 v[162:163], v[132:133], off offset:48
	global_load_dwordx2 v[154:155], v[12:13], off offset:96
	global_load_dwordx2 v[164:165], v[12:13], off offset:112
	global_load_dwordx4 v[4:7], v[148:149], off offset:1024
	global_load_dwordx2 v[138:139], v[132:133], off offset:64
	global_load_dwordx2 v[146:147], v[132:133], off offset:80
	global_load_dwordx2 v[158:159], v[132:133], off offset:96
	global_load_dwordx2 v[166:167], v[132:133], off offset:112
	v_lshlrev_b64 v[8:9], 15, v[8:9]
	v_readlane_b32 s9, v253, 22
	v_mov_b32_e32 v11, v131
	v_mov_b32_e32 v19, v131
	v_lshl_add_u64 v[8:9], s[8:9], 0, v[8:9]
	v_lshl_add_u64 v[24:25], v[10:11], 3, v[8:9]
	v_lshl_add_u64 v[26:27], v[16:17], 0, v[18:19]
	global_load_dwordx4 v[8:11], v[148:149], off offset:2048
	global_load_dwordx2 v[168:169], v[24:25], off
	global_load_dword v218, v[22:23], off offset:4
	global_load_dwordx2 v[140:141], v[12:13], off
	global_load_dwordx2 v[156:157], v[12:13], off offset:16
	global_load_dwordx4 v[16:19], v[148:149], off offset:3072
	v_readlane_b32 s8, v253, 27
	v_readlane_b32 s9, v253, 28
	v_lshl_add_u64 v[12:13], v[26:27], 0, v[20:21]
	global_load_dwordx4 v[108:111], v[12:13], off offset:3072
	global_load_dwordx4 v[104:107], v[12:13], off offset:2048
	global_load_dwordx4 v[100:103], v[12:13], off offset:1024
	global_load_dwordx4 v[96:99], v[12:13], off
	v_lshl_add_u64 v[14:15], s[8:9], 0, v[14:15]
	v_lshl_add_u64 v[170:171], v[14:15], 0, v[130:131]
	global_load_dwordx2 v[114:115], v[170:171], off offset:3584
	global_load_dwordx2 v[112:113], v[170:171], off offset:3072
	global_load_dwordx2 v[118:119], v[170:171], off offset:2560
	global_load_dwordx2 v[116:117], v[170:171], off offset:2048
	global_load_dwordx2 v[122:123], v[170:171], off offset:1536
	global_load_dwordx2 v[120:121], v[170:171], off offset:1024
	global_load_dwordx2 v[126:127], v[170:171], off offset:512
	global_load_dwordx2 v[124:125], v[170:171], off
	s_mov_b32 s56, 0
	s_mov_b32 s57, s56
	s_mov_b32 s58, s56
	s_mov_b32 s59, s56
	s_mov_b32 s60, s56
	s_mov_b32 s61, s56
	s_mov_b32 s62, s56
	s_mov_b32 s63, s56
	s_mov_b32 s64, s56
	s_mov_b32 s65, s56
	s_mov_b32 s66, s56
	s_mov_b32 s67, s56
	s_mov_b32 s68, s56
	s_mov_b32 s69, s56
	s_waitcnt vmcnt(36)
; #define MFMA32(a, b, c) __builtin_amdgcn_mfma_f32_32x32x16_bf16((a), (b), (c), 0, 0, 0)
; template <class KP, class VP, class ACT, class FILL>
; DI void attn_loop(AttnSt& st, const bf16x8 (&qf)[4], int k0, int k1, size_t vstride, KP kp, VP vp, ACT act, FILL fill) {
;   KVT cur, nxt;
;   {
;     KVT t0; load_kv(t0, kp(k0), vp(k0), vstride);
; #pragma unroll
;     for (int i = 0; i < 8; ++i) cur.v[i] = t0.v[i];
; #pragma unroll
;     for (int i = 0; i < 4; ++i) cur.k[i] = t0.k[i];
;   }
;   f32x16 s_cur;
;   { const float z = 0.f;
; #pragma unroll
;     for (int i = 0; i < 16; ++i) s_cur[i] = z; }
; #pragma unroll
;   for (int ss = 0; ss < 4; ++ss) s_cur = MFMA32(cur.k[ss], qf[ss], s_cur);
;   {
;     const int kn = (k0 < k1) ? k0 + 1 : k1;
;     const bf16_t* krow = kp(kn);
; #pragma unroll
;     for (int ss = 0; ss < 4; ++ss) nxt.k[ss] = *(const bf16x8*)(krow + 512 * ss);
;   }
	v_mfma_f32_32x32x16_bf16 v[48:63], v[0:3], v[80:83], 0
	s_mov_b32 s70, s56
	s_mov_b32 s71, s56
	v_lshlrev_b32_e32 v20, 2, v30
	v_lshl_add_u32 v219, v28, 7, 0
	v_subrev_u32_e32 v220, 31, v31
	v_sub_u32_e32 v221, v29, v20
	v_mov_b32_e32 v222, 0
	s_waitcnt vmcnt(22)
	v_mfma_f32_32x32x16_bf16 v[48:63], v[4:7], v[84:87], v[48:63]
	v_mov_b32_e32 v223, 0xff800000
	s_waitcnt vmcnt(17)
	v_mfma_f32_32x32x16_bf16 v[48:63], v[8:11], v[88:91], v[48:63]
	v_mov_b64_e32 v[0:1], s[56:57]
	v_mov_b64_e32 v[14:15], s[70:71]
	v_mov_b64_e32 v[2:3], s[58:59]
	v_mov_b64_e32 v[4:5], s[60:61]
	v_mov_b64_e32 v[6:7], s[62:63]
	v_mov_b64_e32 v[8:9], s[64:65]
	v_mov_b64_e32 v[10:11], s[66:67]
	s_waitcnt vmcnt(12)
	v_mfma_f32_32x32x16_bf16 v[48:63], v[16:19], v[92:95], v[48:63]
	v_mov_b64_e32 v[12:13], s[68:69]
	v_mov_b64_e32 v[30:31], v[14:15]
	s_mov_b64 s[58:59], 0
	v_mov_b64_e32 v[28:29], v[12:13]
	v_mov_b64_e32 v[26:27], v[10:11]
	v_mov_b64_e32 v[24:25], v[8:9]
	v_mov_b64_e32 v[22:23], v[6:7]
	v_mov_b64_e32 v[20:21], v[4:5]
	v_mov_b64_e32 v[18:19], v[2:3]
	v_mov_b64_e32 v[16:17], v[0:1]
	s_waitcnt vmcnt(0)
	v_readfirstlane_b32 s60, v217
	v_lshrrev_b32_e32 v246, 6, v129
	v_and_b32_e32 v247, 63, v129
	v_lshlrev_b32_e32 v247, 3, v247
	v_readfirstlane_b32 s58, v246
	v_mov_b32_e32 v224, s60
	v_mov_b32_e32 v225, 0x1940
	v_lshl_add_u32 v234, v246, 2, v225
	ds_write_b32 v234, v224
	s_waitcnt lgkmcnt(0)
	s_barrier
	ds_read_b128 v[226:229], v225
	ds_read_b128 v[230:233], v225 offset:16
	s_waitcnt lgkmcnt(0)
	v_max3_u32 v226, v226, v227, v228
	v_max3_u32 v226, v226, v229, v230
	v_max3_u32 v226, v226, v231, v232
	v_max_u32_e32 v226, v226, v233
	s_nop 0
	v_readfirstlane_b32 s59, v226
	s_mov_b32 s56, 0
	s_mov_b32 s23, 0
	s_mov_b32 s100, 0x10000
	s_lshr_b32 s24, s59, 1
	s_min_u32 s24, s23, s24
	s_lshl_b32 s26, s24, 13
	s_lshl_b32 s24, s58, 10
	s_add_u32 s26, s26, s24
	s_mov_b32 s27, 0
	v_lshl_add_u64 v[248:249], v[148:149], 0, s[26:27]
	v_lshl_add_u64 v[250:251], v[170:171], 0, s[26:27]
	v_add_co_u32_e32 v250, vcc, v250, v247
	v_addc_co_u32_e32 v251, vcc, 0, v251, vcc
	s_add_u32 s24, s24, s100
	s_mov_b32 m0, s24
	s_nop 0
	global_load_lds_dwordx4 v[248:249], off
	s_add_u32 s24, s24, 0x2000
	s_mov_b32 m0, s24
	s_nop 0
	global_load_lds_dwordx4 v[250:251], off
	s_lshr_b32 s24, s59, 1
	s_add_u32 s23, s23, 1
	s_min_u32 s24, s23, s24
	s_lshl_b32 s26, s24, 13
	s_lshl_b32 s24, s58, 10
	s_add_u32 s26, s26, s24
	s_mov_b32 s27, 0
	v_lshl_add_u64 v[248:249], v[148:149], 0, s[26:27]
	v_lshl_add_u64 v[250:251], v[170:171], 0, s[26:27]
	v_add_co_u32_e32 v250, vcc, v250, v247
	v_addc_co_u32_e32 v251, vcc, 0, v251, vcc
	s_add_u32 s24, s24, s100
	s_add_u32 s24, s24, 0x4000
	s_mov_b32 m0, s24
	s_nop 0
	global_load_lds_dwordx4 v[248:249], off
	s_add_u32 s24, s24, 0x2000
	s_mov_b32 m0, s24
	s_nop 0
	global_load_lds_dwordx4 v[250:251], off
	v_lshrrev_b32_e32 v246, 6, v129
	v_mul_u32_u24_e32 v246, 6912, v246
	v_add_u32_e32 v242, 8192, v246
	v_and_b32_e32 v246, 63, v129
	v_add_u32_e32 v224, -64, v246
	v_mov_b32_e32 v224, 0
	v_mov_b32_e32 v225, v246
	v_add_u32_e32 v226, 64, v246
	v_add_u32_e32 v227, 128, v246
	v_add_u32_e32 v228, 192, v246
	v_add_u32_e32 v229, 256, v246
	v_add_u32_e32 v230, 320, v246
	v_add_u32_e32 v231, 384, v246
	v_add_u32_e32 v232, 448, v246
	ds_read_u8 v224, v224
	ds_read_u8 v225, v225
	ds_read_u8 v226, v226
	ds_read_u8 v227, v227
	ds_read_u8 v228, v228
	ds_read_u8 v229, v229
	ds_read_u8 v230, v230
	ds_read_u8 v231, v231
	ds_read_u8 v232, v232
	s_waitcnt lgkmcnt(8)
	v_lshl_add_u32 v224, v224, 2, v219
	s_waitcnt lgkmcnt(7)
	v_lshl_add_u32 v225, v225, 2, v219
	s_waitcnt lgkmcnt(6)
	v_lshl_add_u32 v226, v226, 2, v219
	s_waitcnt lgkmcnt(5)
	v_lshl_add_u32 v227, v227, 2, v219
	s_waitcnt lgkmcnt(4)
	v_lshl_add_u32 v228, v228, 2, v219
	s_waitcnt lgkmcnt(3)
	v_lshl_add_u32 v229, v229, 2, v219
	s_waitcnt lgkmcnt(2)
	v_lshl_add_u32 v230, v230, 2, v219
	s_waitcnt lgkmcnt(1)
	v_lshl_add_u32 v231, v231, 2, v219
	s_waitcnt lgkmcnt(0)
	v_lshl_add_u32 v232, v232, 2, v219
	ds_read_b32 v224, v224 offset:4096
	ds_read_b32 v225, v225 offset:4096
	ds_read_b32 v226, v226 offset:4096
	ds_read_b32 v227, v227 offset:4096
	ds_read_b32 v228, v228 offset:4096
	ds_read_b32 v229, v229 offset:4096
	ds_read_b32 v230, v230 offset:4096
	ds_read_b32 v231, v231 offset:4096
	ds_read_b32 v232, v232 offset:4096
	v_lshl_add_u32 v244, v246, 2, v242
	s_waitcnt lgkmcnt(8)
	ds_write_b32 v244, v224 offset:0
	s_waitcnt lgkmcnt(7)
	ds_write_b32 v244, v225 offset:256
	s_waitcnt lgkmcnt(6)
	ds_write_b32 v244, v226 offset:512
	s_waitcnt lgkmcnt(5)
	ds_write_b32 v244, v227 offset:768
	s_waitcnt lgkmcnt(4)
	ds_write_b32 v244, v228 offset:1024
	s_waitcnt lgkmcnt(3)
	ds_write_b32 v244, v229 offset:1280
	s_waitcnt lgkmcnt(2)
	ds_write_b32 v244, v230 offset:1536
	s_waitcnt lgkmcnt(1)
	ds_write_b32 v244, v231 offset:1792
	s_waitcnt lgkmcnt(0)
	ds_write_b32 v244, v232 offset:2048
	v_add_u32_e32 v224, 512, v246
	v_add_u32_e32 v225, 576, v246
	v_add_u32_e32 v226, 640, v246
	v_add_u32_e32 v227, 704, v246
	v_add_u32_e32 v228, 768, v246
	v_add_u32_e32 v229, 832, v246
	v_add_u32_e32 v230, 896, v246
	v_add_u32_e32 v231, 960, v246
	v_add_u32_e32 v232, 1024, v246
	ds_read_u8 v224, v224
	ds_read_u8 v225, v225
	ds_read_u8 v226, v226
	ds_read_u8 v227, v227
	ds_read_u8 v228, v228
	ds_read_u8 v229, v229
	ds_read_u8 v230, v230
	ds_read_u8 v231, v231
	ds_read_u8 v232, v232
	s_waitcnt lgkmcnt(8)
	v_lshl_add_u32 v224, v224, 2, v219
	s_waitcnt lgkmcnt(7)
	v_lshl_add_u32 v225, v225, 2, v219
	s_waitcnt lgkmcnt(6)
	v_lshl_add_u32 v226, v226, 2, v219
	s_waitcnt lgkmcnt(5)
	v_lshl_add_u32 v227, v227, 2, v219
	s_waitcnt lgkmcnt(4)
	v_lshl_add_u32 v228, v228, 2, v219
	s_waitcnt lgkmcnt(3)
; #define MFMA32(a, b, c) __builtin_amdgcn_mfma_f32_32x32x16_bf16((a), (b), (c), 0, 0, 0)
; template <class KP, class VP, class ACT, class FILL>
; DI void attn_loop(AttnSt& st, const bf16x8 (&qf)[4], int k0, int k1, size_t vstride, KP kp, VP vp, ACT act, FILL fill) {
;     ...
;   for (int kt = k0; kt <= k1; ++kt) {
;     const int kn = (kt < k1) ? kt + 1 : k1;
;     const int kn2 = (kt + 2 <= k1) ? kt + 2 : k1;
;     {
;       const bf16_t* v0 = vp(kn);
; #pragma unroll
;       for (int j = 0; j < 8; ++j) nxt.v[j] = *(const s16x4*)(v0 + 256 * j);
;     }
;     bf16x8 k2[4];
;     {
;       const bf16_t* krow = kp(kn2);
; #pragma unroll
;       for (int ss = 0; ss < 4; ++ss) k2[ss] = *(const bf16x8*)(krow + 512 * ss);
;     }
;     f32x16 s_next;
; #pragma unroll
;     for (int i = 0; i < 16; ++i) s_next[i] = 0.f;
; #pragma unroll
;     for (int ss = 0; ss < 4; ++ss) s_next = MFMA32(nxt.k[ss], qf[ss], s_next);
; DI void nsa_main_item(const Params& p, int b, int head, int qb, const unsigned char* blut, const float* tbl) {
;     ...
;     attn_loop(st, qf, 0, qb, 32,
;       [&](int kt) { return K + (size_t)kt * 2048 + (h * 32 + r) * 8; },
;       [&](int kt) { return Vt + (size_t)kt * 2048 + (h * 32 + r) * 4; },
;       [&](int kt) { return __ballot((selm >> (kt >> 1)) & 1ull) != 0ull; },
	v_lshl_add_u32 v229, v229, 2, v219
	s_waitcnt lgkmcnt(2)
	v_lshl_add_u32 v230, v230, 2, v219
	s_waitcnt lgkmcnt(1)
	v_lshl_add_u32 v231, v231, 2, v219
	s_waitcnt lgkmcnt(0)
	v_lshl_add_u32 v232, v232, 2, v219
	ds_read_b32 v224, v224 offset:4096
	ds_read_b32 v225, v225 offset:4096
	ds_read_b32 v226, v226 offset:4096
	ds_read_b32 v227, v227 offset:4096
	ds_read_b32 v228, v228 offset:4096
	ds_read_b32 v229, v229 offset:4096
	ds_read_b32 v230, v230 offset:4096
	ds_read_b32 v231, v231 offset:4096
	ds_read_b32 v232, v232 offset:4096
	v_lshl_add_u32 v244, v246, 2, v242
	s_waitcnt lgkmcnt(8)
	ds_write_b32 v244, v224 offset:2304
	s_waitcnt lgkmcnt(7)
	ds_write_b32 v244, v225 offset:2560
	s_waitcnt lgkmcnt(6)
	ds_write_b32 v244, v226 offset:2816
	s_waitcnt lgkmcnt(5)
	ds_write_b32 v244, v227 offset:3072
	s_waitcnt lgkmcnt(4)
	ds_write_b32 v244, v228 offset:3328
	s_waitcnt lgkmcnt(3)
	ds_write_b32 v244, v229 offset:3584
	s_waitcnt lgkmcnt(2)
	ds_write_b32 v244, v230 offset:3840
	s_waitcnt lgkmcnt(1)
	ds_write_b32 v244, v231 offset:4096
	s_waitcnt lgkmcnt(0)
	ds_write_b32 v244, v232 offset:4352
	v_add_u32_e32 v224, 1088, v246
	v_add_u32_e32 v225, 1152, v246
	v_add_u32_e32 v226, 1216, v246
	v_add_u32_e32 v227, 1280, v246
	v_add_u32_e32 v228, 1344, v246
	v_add_u32_e32 v229, 1408, v246
	v_add_u32_e32 v230, 1472, v246
	v_add_u32_e32 v231, 1536, v246
	v_add_u32_e32 v232, 1600, v246
	ds_read_u8 v224, v224
	ds_read_u8 v225, v225
	ds_read_u8 v226, v226
	ds_read_u8 v227, v227
	ds_read_u8 v228, v228
	ds_read_u8 v229, v229
	ds_read_u8 v230, v230
	ds_read_u8 v231, v231
	ds_read_u8 v232, v232
	s_waitcnt lgkmcnt(8)
	v_lshl_add_u32 v224, v224, 2, v219
	s_waitcnt lgkmcnt(7)
	v_lshl_add_u32 v225, v225, 2, v219
	s_waitcnt lgkmcnt(6)
	v_lshl_add_u32 v226, v226, 2, v219
	s_waitcnt lgkmcnt(5)
	v_lshl_add_u32 v227, v227, 2, v219
	s_waitcnt lgkmcnt(4)
	v_lshl_add_u32 v228, v228, 2, v219
	s_waitcnt lgkmcnt(3)
	v_lshl_add_u32 v229, v229, 2, v219
	s_waitcnt lgkmcnt(2)
	v_lshl_add_u32 v230, v230, 2, v219
	s_waitcnt lgkmcnt(1)
	v_lshl_add_u32 v231, v231, 2, v219
	s_waitcnt lgkmcnt(0)
	v_lshl_add_u32 v232, v232, 2, v219
	ds_read_b32 v224, v224 offset:4096
	ds_read_b32 v225, v225 offset:4096
	ds_read_b32 v226, v226 offset:4096
	ds_read_b32 v227, v227 offset:4096
	ds_read_b32 v228, v228 offset:4096
	ds_read_b32 v229, v229 offset:4096
	ds_read_b32 v230, v230 offset:4096
	ds_read_b32 v231, v231 offset:4096
	ds_read_b32 v232, v232 offset:4096
	v_lshl_add_u32 v244, v246, 2, v242
	s_waitcnt lgkmcnt(8)
	ds_write_b32 v244, v224 offset:4608
	s_waitcnt lgkmcnt(7)
	ds_write_b32 v244, v225 offset:4864
	s_waitcnt lgkmcnt(6)
	ds_write_b32 v244, v226 offset:5120
	s_waitcnt lgkmcnt(5)
	ds_write_b32 v244, v227 offset:5376
	s_waitcnt lgkmcnt(4)
	ds_write_b32 v244, v228 offset:5632
	s_waitcnt lgkmcnt(3)
	ds_write_b32 v244, v229 offset:5888
	s_waitcnt lgkmcnt(2)
	ds_write_b32 v244, v230 offset:6144
	s_waitcnt lgkmcnt(1)
	ds_write_b32 v244, v231 offset:6400
	s_waitcnt lgkmcnt(0)
	ds_write_b32 v244, v232 offset:6656
	ds_read_b32 v240, v219 offset:4220
	v_add_u32_e32 v242, 148, v242
	v_mov_b32_e32 v243, 0x7f800000
	s_waitcnt lgkmcnt(0)
.Lasel_loop:
	s_waitcnt vmcnt(0)
	s_barrier
	s_lshr_b32 s23, s56, 1
	s_add_u32 s23, s23, 2
	s_xor_b32 s61, s100, 0x8000
	s_lshr_b32 s24, s59, 1
	s_min_u32 s24, s23, s24
	s_lshl_b32 s26, s24, 13
	s_lshl_b32 s24, s58, 10
	s_add_u32 s26, s26, s24
	s_mov_b32 s27, 0
	v_lshl_add_u64 v[248:249], v[148:149], 0, s[26:27]
	v_lshl_add_u64 v[250:251], v[170:171], 0, s[26:27]
	v_add_co_u32_e32 v250, vcc, v250, v247
	v_addc_co_u32_e32 v251, vcc, 0, v251, vcc
	s_add_u32 s24, s24, s61
	s_mov_b32 m0, s24
	s_nop 0
	global_load_lds_dwordx4 v[248:249], off
	s_add_u32 s24, s24, 0x2000
	s_mov_b32 m0, s24
	s_nop 0
	global_load_lds_dwordx4 v[250:251], off
	s_lshr_b32 s24, s59, 1
	s_add_u32 s23, s23, 1
	s_min_u32 s24, s23, s24
	s_lshl_b32 s26, s24, 13
	s_lshl_b32 s24, s58, 10
	s_add_u32 s26, s26, s24
	s_mov_b32 s27, 0
	v_lshl_add_u64 v[248:249], v[148:149], 0, s[26:27]
	v_lshl_add_u64 v[250:251], v[170:171], 0, s[26:27]
	v_add_co_u32_e32 v250, vcc, v250, v247
	v_addc_co_u32_e32 v251, vcc, 0, v251, vcc
	s_add_u32 s24, s24, s61
	s_add_u32 s24, s24, 0x4000
	s_mov_b32 m0, s24
	s_nop 0
	global_load_lds_dwordx4 v[248:249], off
	s_add_u32 s24, s24, 0x2000
	s_mov_b32 m0, s24
	s_nop 0
	global_load_lds_dwordx4 v[250:251], off
	s_cmp_le_u32 s56, s60
	s_cbranch_scc0 .Lasel_skipa
	v_lshl_add_u32 v248, v247, 1, s100
	ds_read_b128 v[96:99], v248 offset:0
	ds_read_b128 v[100:103], v248 offset:1024
	ds_read_b128 v[104:107], v248 offset:2048
	ds_read_b128 v[108:111], v248 offset:3072
	ds_read_b128 v[112:115], v248 offset:4096
	ds_read_b128 v[116:119], v248 offset:5120
	ds_read_b128 v[120:123], v248 offset:6144
	ds_read_b128 v[124:127], v248 offset:7168
	s_sub_i32 s61, s60, s56
	s_lshr_b32 s23, s56, 1
	v_lshrrev_b64 v[248:249], s23, v[168:169]
	v_and_b32_e32 v248, 1, v248
	v_cmp_eq_u32_e64 s[62:63], 1, v248
	s_waitcnt lgkmcnt(0)
	v_mfma_f32_32x32x16_bf16 v[32:47], v[96:99], v[80:83], 0
	v_mfma_f32_32x32x16_bf16 v[48:63], v[112:115], v[80:83], 0
	v_mfma_f32_32x32x16_bf16 v[32:47], v[100:103], v[84:87], v[32:47]
	v_mfma_f32_32x32x16_bf16 v[48:63], v[116:119], v[84:87], v[48:63]
	v_mfma_f32_32x32x16_bf16 v[32:47], v[104:107], v[88:91], v[32:47]
	v_mfma_f32_32x32x16_bf16 v[48:63], v[120:123], v[88:91], v[48:63]
	v_mfma_f32_32x32x16_bf16 v[32:47], v[108:111], v[92:95], v[32:47]
	v_mfma_f32_32x32x16_bf16 v[48:63], v[124:127], v[92:95], v[48:63]
	v_add_u32_e32 v250, s100, v247
	ds_read_b64 v[64:65], v250 offset:8192
	ds_read_b64 v[66:67], v250 offset:8704
	ds_read_b64 v[68:69], v250 offset:9216
	ds_read_b64 v[70:71], v250 offset:9728
	ds_read_b64 v[72:73], v250 offset:10240
	ds_read_b64 v[74:75], v250 offset:10752
	ds_read_b64 v[76:77], v250 offset:11264
	ds_read_b64 v[78:79], v250 offset:11776
	ds_read_b64 v[172:173], v250 offset:12288
	ds_read_b64 v[174:175], v250 offset:12800
	ds_read_b64 v[176:177], v250 offset:13312
	ds_read_b64 v[178:179], v250 offset:13824
	ds_read_b64 v[180:181], v250 offset:14336
	ds_read_b64 v[182:183], v250 offset:14848
	ds_read_b64 v[184:185], v250 offset:15360
	ds_read_b64 v[186:187], v250 offset:15872
	s_cmp_ge_i32 s61, 50
	s_cbranch_scc1 .Lasel_fara
; #define NEGINF (-__builtin_inff())
; DI int crow(int i, int h) { return (i & 3) + 8 * (i >> 2) + 4 * h; }
; DI void nsa_main_item(const Params& p, int b, int head, int qb, const unsigned char* blut, const float* tbl) {
;     ...
;           int dist[16]; float bv[16];
; #pragma unroll
;           for (int i = 0; i < 16; ++i) dist[i] = t - (kt * 32 + crow(i, h));
;           bias16(blut, tblh, dist, bv);
; #pragma unroll
;           for (int i = 0; i < 16; ++i) lg[i] = (bs && dist[i] >= 0) ? s[i] + bv[i] : NEGINF;
;         }
	s_lshl_b32 s23, s61, 5
	v_add_u32_e32 v241, s23, v221
	v_lshl_add_u32 v244, v241, 2, v242
	v_subrev_u32_e32 v245, 128, v244
	ds_read_b32 v224, v244 offset:108
	ds_read_b32 v225, v244 offset:104
	ds_read_b32 v226, v244 offset:100
	ds_read_b32 v227, v244 offset:96
	ds_read_b32 v228, v244 offset:76
	ds_read_b32 v229, v244 offset:72
	ds_read_b32 v230, v244 offset:68
	ds_read_b32 v231, v244 offset:64
	ds_read_b32 v232, v244 offset:44
	ds_read_b32 v233, v244 offset:40
	ds_read_b32 v234, v244 offset:36
	ds_read_b32 v235, v244 offset:32
	ds_read_b32 v236, v244 offset:12
	ds_read_b32 v237, v244 offset:8
	ds_read_b32 v238, v244 offset:4
	ds_read_b32 v239, v244 offset:0
	s_waitcnt lgkmcnt(8)
	v_add_f32_e32 v32, v32, v224
	v_add_f32_e32 v33, v33, v225
	v_add_f32_e32 v34, v34, v226
	v_add_f32_e32 v35, v35, v227
	v_add_f32_e32 v36, v36, v228
	v_add_f32_e32 v37, v37, v229
	v_add_f32_e32 v38, v38, v230
	v_add_f32_e32 v39, v39, v231
	s_waitcnt lgkmcnt(0)
	v_add_f32_e32 v40, v40, v232
	v_add_f32_e32 v41, v41, v233
	v_add_f32_e32 v42, v42, v234
	v_add_f32_e32 v43, v43, v235
	v_add_f32_e32 v44, v44, v236
	v_add_f32_e32 v45, v45, v237
	v_add_f32_e32 v46, v46, v238
	v_add_f32_e32 v47, v47, v239
	ds_read_b32 v224, v245 offset:108
	ds_read_b32 v225, v245 offset:104
	ds_read_b32 v226, v245 offset:100
	ds_read_b32 v227, v245 offset:96
	ds_read_b32 v228, v245 offset:76
	ds_read_b32 v229, v245 offset:72
	ds_read_b32 v230, v245 offset:68
	ds_read_b32 v231, v245 offset:64
	ds_read_b32 v232, v245 offset:44
	ds_read_b32 v233, v245 offset:40
	ds_read_b32 v234, v245 offset:36
	ds_read_b32 v235, v245 offset:32
	ds_read_b32 v236, v245 offset:12
	ds_read_b32 v237, v245 offset:8
	ds_read_b32 v238, v245 offset:4
	ds_read_b32 v239, v245 offset:0
	s_waitcnt lgkmcnt(8)
	v_add_f32_e32 v48, v48, v224
	v_add_f32_e32 v49, v49, v225
	v_add_f32_e32 v50, v50, v226
	v_add_f32_e32 v51, v51, v227
	v_add_f32_e32 v52, v52, v228
	v_add_f32_e32 v53, v53, v229
	v_add_f32_e32 v54, v54, v230
	v_add_f32_e32 v55, v55, v231
	s_waitcnt lgkmcnt(0)
	v_add_f32_e32 v56, v56, v232
	v_add_f32_e32 v57, v57, v233
	v_add_f32_e32 v58, v58, v234
	v_add_f32_e32 v59, v59, v235
	v_add_f32_e32 v60, v60, v236
	v_add_f32_e32 v61, v61, v237
	v_add_f32_e32 v62, v62, v238
	v_add_f32_e32 v63, v63, v239
	s_cmp_ge_i32 s61, 2
	s_cbranch_scc1 .Lasel_softmaxa
	v_subrev_u32_e32 v246, 32, v241
	v_cmp_le_i32_e32 vcc, 0, v241
	s_nop 1
	v_cndmask_b32_e32 v32, v199, v32, vcc
	v_cmp_le_i32_e32 vcc, 1, v241
	s_nop 1
	v_cndmask_b32_e32 v33, v199, v33, vcc
	v_cmp_le_i32_e32 vcc, 2, v241
	s_nop 1
	v_cndmask_b32_e32 v34, v199, v34, vcc
	v_cmp_le_i32_e32 vcc, 3, v241
	s_nop 1
	v_cndmask_b32_e32 v35, v199, v35, vcc
	v_cmp_le_i32_e32 vcc, 8, v241
	s_nop 1
	v_cndmask_b32_e32 v36, v199, v36, vcc
	v_cmp_le_i32_e32 vcc, 9, v241
	s_nop 1
	v_cndmask_b32_e32 v37, v199, v37, vcc
	v_cmp_le_i32_e32 vcc, 10, v241
	s_nop 1
	v_cndmask_b32_e32 v38, v199, v38, vcc
	v_cmp_le_i32_e32 vcc, 11, v241
	s_nop 1
	v_cndmask_b32_e32 v39, v199, v39, vcc
	v_cmp_le_i32_e32 vcc, 16, v241
	s_nop 1
	v_cndmask_b32_e32 v40, v199, v40, vcc
	v_cmp_le_i32_e32 vcc, 17, v241
	s_nop 1
	v_cndmask_b32_e32 v41, v199, v41, vcc
	v_cmp_le_i32_e32 vcc, 18, v241
	s_nop 1
	v_cndmask_b32_e32 v42, v199, v42, vcc
	v_cmp_le_i32_e32 vcc, 19, v241
	s_nop 1
	v_cndmask_b32_e32 v43, v199, v43, vcc
	v_cmp_le_i32_e32 vcc, 24, v241
	s_nop 1
	v_cndmask_b32_e32 v44, v199, v44, vcc
	v_cmp_le_i32_e32 vcc, 25, v241
	s_nop 1
	v_cndmask_b32_e32 v45, v199, v45, vcc
	v_cmp_le_i32_e32 vcc, 26, v241
	s_nop 1
	v_cndmask_b32_e32 v46, v199, v46, vcc
	v_cmp_le_i32_e32 vcc, 27, v241
	s_nop 1
	v_cndmask_b32_e32 v47, v199, v47, vcc
	v_cmp_le_i32_e32 vcc, 0, v246
	s_nop 1
	v_cndmask_b32_e32 v48, v199, v48, vcc
	v_cmp_le_i32_e32 vcc, 1, v246
	s_nop 1
	v_cndmask_b32_e32 v49, v199, v49, vcc
	v_cmp_le_i32_e32 vcc, 2, v246
	s_nop 1
	v_cndmask_b32_e32 v50, v199, v50, vcc
	v_cmp_le_i32_e32 vcc, 3, v246
	s_nop 1
	v_cndmask_b32_e32 v51, v199, v51, vcc
	v_cmp_le_i32_e32 vcc, 8, v246
	s_nop 1
	v_cndmask_b32_e32 v52, v199, v52, vcc
	v_cmp_le_i32_e32 vcc, 9, v246
	s_nop 1
	v_cndmask_b32_e32 v53, v199, v53, vcc
	v_cmp_le_i32_e32 vcc, 10, v246
	s_nop 1
	v_cndmask_b32_e32 v54, v199, v54, vcc
	v_cmp_le_i32_e32 vcc, 11, v246
	s_nop 1
	v_cndmask_b32_e32 v55, v199, v55, vcc
	v_cmp_le_i32_e32 vcc, 16, v246
	s_nop 1
	v_cndmask_b32_e32 v56, v199, v56, vcc
	v_cmp_le_i32_e32 vcc, 17, v246
	s_nop 1
	v_cndmask_b32_e32 v57, v199, v57, vcc
	v_cmp_le_i32_e32 vcc, 18, v246
	s_nop 1
	v_cndmask_b32_e32 v58, v199, v58, vcc
	v_cmp_le_i32_e32 vcc, 19, v246
	s_nop 1
	v_cndmask_b32_e32 v59, v199, v59, vcc
	v_cmp_le_i32_e32 vcc, 24, v246
	s_nop 1
	v_cndmask_b32_e32 v60, v199, v60, vcc
	v_cmp_le_i32_e32 vcc, 25, v246
	s_nop 1
	v_cndmask_b32_e32 v61, v199, v61, vcc
	v_cmp_le_i32_e32 vcc, 26, v246
	s_nop 1
	v_cndmask_b32_e32 v62, v199, v62, vcc
	v_cmp_le_i32_e32 vcc, 27, v246
	s_nop 1
	v_cndmask_b32_e32 v63, v199, v63, vcc
	s_branch .Lasel_softmaxa

; #define MFMA32(a, b, c) __builtin_amdgcn_mfma_f32_32x32x16_bf16((a), (b), (c), 0, 0, 0)
; #define NEGINF (-__builtin_inff())
; DI int crow(int i, int h) { return (i & 3) + 8 * (i >> 2) + 4 * h; }
; template <class KP, class VP, class ACT, class FILL>
; DI void attn_loop(AttnSt& st, const bf16x8 (&qf)[4], int k0, int k1, size_t vstride, KP kp, VP vp, ACT act, FILL fill) {
;     ...
;   for (int kt = k0; kt <= k1; ++kt) {
;     const int kn = (kt < k1) ? kt + 1 : k1;
;     const int kn2 = (kt + 2 <= k1) ? kt + 2 : k1;
;     {
;       const bf16_t* v0 = vp(kn);
; #pragma unroll
;       for (int j = 0; j < 8; ++j) nxt.v[j] = *(const s16x4*)(v0 + 256 * j);
;     }
;     bf16x8 k2[4];
;     {
;       const bf16_t* krow = kp(kn2);
; #pragma unroll
;       for (int ss = 0; ss < 4; ++ss) k2[ss] = *(const bf16x8*)(krow + 512 * ss);
;     }
;     f32x16 s_next;
; #pragma unroll
;     for (int i = 0; i < 16; ++i) s_next[i] = 0.f;
; #pragma unroll
;     for (int ss = 0; ss < 4; ++ss) s_next = MFMA32(nxt.k[ss], qf[ss], s_next);
;     if (act(kt)) {
;       float lg[16];
;       fill(kt, s_cur, lg);
;       softmax_step_r(st, lg, cur);
;     }
;     s_cur = s_next;
; #pragma unroll
;     for (int i = 0; i < 8; ++i) cur.v[i] = nxt.v[i];
; #pragma unroll
;     for (int ss = 0; ss < 4; ++ss) nxt.k[ss] = k2[ss];
;   }
; DI void nsa_main_item(const Params& p, int b, int head, int qb, const unsigned char* blut, const float* tbl) {
;     ...
;       [&](int kt, const f32x16& s, float (&lg)[16]) {
;         const bool bs = (selm >> (kt >> 1)) & 1ull;
;         if (qb * 32 - (kt * 32 + 31) >= 1513) {
;           const float b31 = tblh[31];
; #pragma unroll
;           for (int i = 0; i < 16; ++i) lg[i] = bs ? s[i] + b31 : NEGINF;
;         } else {
;           int dist[16]; float bv[16];
; #pragma unroll
;           for (int i = 0; i < 16; ++i) dist[i] = t - (kt * 32 + crow(i, h));
;           bias16(blut, tblh, dist, bv);
; #pragma unroll
;           for (int i = 0; i < 16; ++i) lg[i] = (bs && dist[i] >= 0) ? s[i] + bv[i] : NEGINF;
;         }
.Lasel_skipa:
	s_add_u32 s24, s56, 2
	s_cmp_le_u32 s24, s60
	s_cbranch_scc0 .Lasel_skipb
	v_lshl_add_u32 v248, v247, 1, s100
	ds_read_b128 v[96:99], v248 offset:16384
	ds_read_b128 v[100:103], v248 offset:17408
	ds_read_b128 v[104:107], v248 offset:18432
	ds_read_b128 v[108:111], v248 offset:19456
	ds_read_b128 v[112:115], v248 offset:20480
	ds_read_b128 v[116:119], v248 offset:21504
	ds_read_b128 v[120:123], v248 offset:22528
	ds_read_b128 v[124:127], v248 offset:23552
	s_sub_i32 s61, s60, s24
	s_lshr_b32 s23, s24, 1
	v_lshrrev_b64 v[248:249], s23, v[168:169]
	v_and_b32_e32 v248, 1, v248
	v_cmp_eq_u32_e64 s[62:63], 1, v248
	s_waitcnt lgkmcnt(0)
	v_mfma_f32_32x32x16_bf16 v[32:47], v[96:99], v[80:83], 0
	v_mfma_f32_32x32x16_bf16 v[48:63], v[112:115], v[80:83], 0
	v_mfma_f32_32x32x16_bf16 v[32:47], v[100:103], v[84:87], v[32:47]
	v_mfma_f32_32x32x16_bf16 v[48:63], v[116:119], v[84:87], v[48:63]
	v_mfma_f32_32x32x16_bf16 v[32:47], v[104:107], v[88:91], v[32:47]
	v_mfma_f32_32x32x16_bf16 v[48:63], v[120:123], v[88:91], v[48:63]
	v_mfma_f32_32x32x16_bf16 v[32:47], v[108:111], v[92:95], v[32:47]
	v_mfma_f32_32x32x16_bf16 v[48:63], v[124:127], v[92:95], v[48:63]
	v_add_u32_e32 v250, s100, v247
	ds_read_b64 v[64:65], v250 offset:24576
	ds_read_b64 v[66:67], v250 offset:25088
	ds_read_b64 v[68:69], v250 offset:25600
	ds_read_b64 v[70:71], v250 offset:26112
	ds_read_b64 v[72:73], v250 offset:26624
	ds_read_b64 v[74:75], v250 offset:27136
	ds_read_b64 v[76:77], v250 offset:27648
	ds_read_b64 v[78:79], v250 offset:28160
	ds_read_b64 v[172:173], v250 offset:28672
	ds_read_b64 v[174:175], v250 offset:29184
	ds_read_b64 v[176:177], v250 offset:29696
	ds_read_b64 v[178:179], v250 offset:30208
	ds_read_b64 v[180:181], v250 offset:30720
	ds_read_b64 v[182:183], v250 offset:31232
	ds_read_b64 v[184:185], v250 offset:31744
	ds_read_b64 v[186:187], v250 offset:32256
	s_cmp_ge_i32 s61, 50
	s_cbranch_scc1 .Lasel_farb
	s_lshl_b32 s23, s61, 5
	v_add_u32_e32 v241, s23, v221
	v_lshl_add_u32 v244, v241, 2, v242
	v_subrev_u32_e32 v245, 128, v244
	ds_read_b32 v224, v244 offset:108
	ds_read_b32 v225, v244 offset:104
	ds_read_b32 v226, v244 offset:100
	ds_read_b32 v227, v244 offset:96
	ds_read_b32 v228, v244 offset:76
	ds_read_b32 v229, v244 offset:72
	ds_read_b32 v230, v244 offset:68
	ds_read_b32 v231, v244 offset:64
	ds_read_b32 v232, v244 offset:44
	ds_read_b32 v233, v244 offset:40
	ds_read_b32 v234, v244 offset:36
	ds_read_b32 v235, v244 offset:32
	ds_read_b32 v236, v244 offset:12
	ds_read_b32 v237, v244 offset:8
	ds_read_b32 v238, v244 offset:4
	ds_read_b32 v239, v244 offset:0
	s_waitcnt lgkmcnt(8)
	v_add_f32_e32 v32, v32, v224
	v_add_f32_e32 v33, v33, v225
	v_add_f32_e32 v34, v34, v226
	v_add_f32_e32 v35, v35, v227
	v_add_f32_e32 v36, v36, v228
	v_add_f32_e32 v37, v37, v229
	v_add_f32_e32 v38, v38, v230
	v_add_f32_e32 v39, v39, v231
	s_waitcnt lgkmcnt(0)
	v_add_f32_e32 v40, v40, v232
	v_add_f32_e32 v41, v41, v233
	v_add_f32_e32 v42, v42, v234
	v_add_f32_e32 v43, v43, v235
	v_add_f32_e32 v44, v44, v236
	v_add_f32_e32 v45, v45, v237
	v_add_f32_e32 v46, v46, v238
	v_add_f32_e32 v47, v47, v239
	ds_read_b32 v224, v245 offset:108
	ds_read_b32 v225, v245 offset:104
	ds_read_b32 v226, v245 offset:100
	ds_read_b32 v227, v245 offset:96
	ds_read_b32 v228, v245 offset:76
	ds_read_b32 v229, v245 offset:72
	ds_read_b32 v230, v245 offset:68
	ds_read_b32 v231, v245 offset:64
	ds_read_b32 v232, v245 offset:44
	ds_read_b32 v233, v245 offset:40
	ds_read_b32 v234, v245 offset:36
	ds_read_b32 v235, v245 offset:32
	ds_read_b32 v236, v245 offset:12
	ds_read_b32 v237, v245 offset:8
	ds_read_b32 v238, v245 offset:4
	ds_read_b32 v239, v245 offset:0
	s_waitcnt lgkmcnt(8)
	v_add_f32_e32 v48, v48, v224
	v_add_f32_e32 v49, v49, v225
	v_add_f32_e32 v50, v50, v226
	v_add_f32_e32 v51, v51, v227
	v_add_f32_e32 v52, v52, v228
	v_add_f32_e32 v53, v53, v229
	v_add_f32_e32 v54, v54, v230
	v_add_f32_e32 v55, v55, v231
	s_waitcnt lgkmcnt(0)
	v_add_f32_e32 v56, v56, v232
	v_add_f32_e32 v57, v57, v233
	v_add_f32_e32 v58, v58, v234
	v_add_f32_e32 v59, v59, v235
	v_add_f32_e32 v60, v60, v236
	v_add_f32_e32 v61, v61, v237
	v_add_f32_e32 v62, v62, v238
	v_add_f32_e32 v63, v63, v239
	s_cmp_ge_i32 s61, 2
	s_cbranch_scc1 .Lasel_softmaxb
	v_subrev_u32_e32 v246, 32, v241
	v_cmp_le_i32_e32 vcc, 0, v241
	s_nop 1
	v_cndmask_b32_e32 v32, v199, v32, vcc
	v_cmp_le_i32_e32 vcc, 1, v241
	s_nop 1
	v_cndmask_b32_e32 v33, v199, v33, vcc
	v_cmp_le_i32_e32 vcc, 2, v241
	s_nop 1
	v_cndmask_b32_e32 v34, v199, v34, vcc
	v_cmp_le_i32_e32 vcc, 3, v241
	s_nop 1
	v_cndmask_b32_e32 v35, v199, v35, vcc
	v_cmp_le_i32_e32 vcc, 8, v241
	s_nop 1
	v_cndmask_b32_e32 v36, v199, v36, vcc
	v_cmp_le_i32_e32 vcc, 9, v241
	s_nop 1
	v_cndmask_b32_e32 v37, v199, v37, vcc
	v_cmp_le_i32_e32 vcc, 10, v241
	s_nop 1
	v_cndmask_b32_e32 v38, v199, v38, vcc
	v_cmp_le_i32_e32 vcc, 11, v241
	s_nop 1
	v_cndmask_b32_e32 v39, v199, v39, vcc
	v_cmp_le_i32_e32 vcc, 16, v241
	s_nop 1
	v_cndmask_b32_e32 v40, v199, v40, vcc
	v_cmp_le_i32_e32 vcc, 17, v241
	s_nop 1
	v_cndmask_b32_e32 v41, v199, v41, vcc
	v_cmp_le_i32_e32 vcc, 18, v241
	s_nop 1
	v_cndmask_b32_e32 v42, v199, v42, vcc
	v_cmp_le_i32_e32 vcc, 19, v241
	s_nop 1
	v_cndmask_b32_e32 v43, v199, v43, vcc
	v_cmp_le_i32_e32 vcc, 24, v241
	s_nop 1
	v_cndmask_b32_e32 v44, v199, v44, vcc
	v_cmp_le_i32_e32 vcc, 25, v241
	s_nop 1
	v_cndmask_b32_e32 v45, v199, v45, vcc
	v_cmp_le_i32_e32 vcc, 26, v241
	s_nop 1
	v_cndmask_b32_e32 v46, v199, v46, vcc
	v_cmp_le_i32_e32 vcc, 27, v241
	s_nop 1
	v_cndmask_b32_e32 v47, v199, v47, vcc
	v_cmp_le_i32_e32 vcc, 0, v246
	s_nop 1
	v_cndmask_b32_e32 v48, v199, v48, vcc
	v_cmp_le_i32_e32 vcc, 1, v246
	s_nop 1
	v_cndmask_b32_e32 v49, v199, v49, vcc
	v_cmp_le_i32_e32 vcc, 2, v246
	s_nop 1
	v_cndmask_b32_e32 v50, v199, v50, vcc
	v_cmp_le_i32_e32 vcc, 3, v246
	s_nop 1
	v_cndmask_b32_e32 v51, v199, v51, vcc
	v_cmp_le_i32_e32 vcc, 8, v246
	s_nop 1
	v_cndmask_b32_e32 v52, v199, v52, vcc
	v_cmp_le_i32_e32 vcc, 9, v246
	s_nop 1
	v_cndmask_b32_e32 v53, v199, v53, vcc
	v_cmp_le_i32_e32 vcc, 10, v246
	s_nop 1
	v_cndmask_b32_e32 v54, v199, v54, vcc
	v_cmp_le_i32_e32 vcc, 11, v246
	s_nop 1
	v_cndmask_b32_e32 v55, v199, v55, vcc
	v_cmp_le_i32_e32 vcc, 16, v246
	s_nop 1
	v_cndmask_b32_e32 v56, v199, v56, vcc
	v_cmp_le_i32_e32 vcc, 17, v246
	s_nop 1
	v_cndmask_b32_e32 v57, v199, v57, vcc
	v_cmp_le_i32_e32 vcc, 18, v246
	s_nop 1
	v_cndmask_b32_e32 v58, v199, v58, vcc
	v_cmp_le_i32_e32 vcc, 19, v246
	s_nop 1
	v_cndmask_b32_e32 v59, v199, v59, vcc
	v_cmp_le_i32_e32 vcc, 24, v246
	s_nop 1
	v_cndmask_b32_e32 v60, v199, v60, vcc
	v_cmp_le_i32_e32 vcc, 25, v246
	s_nop 1
	v_cndmask_b32_e32 v61, v199, v61, vcc
	v_cmp_le_i32_e32 vcc, 26, v246
	s_nop 1
	v_cndmask_b32_e32 v62, v199, v62, vcc
	v_cmp_le_i32_e32 vcc, 27, v246
	s_nop 1
	v_cndmask_b32_e32 v63, v199, v63, vcc
	s_branch .Lasel_softmaxb

; #define MFMA32(a, b, c) __builtin_amdgcn_mfma_f32_32x32x16_bf16((a), (b), (c), 0, 0, 0)
; template <class KP, class VP, class ACT, class FILL>
; DI void attn_loop(AttnSt& st, const bf16x8 (&qf)[4], int k0, int k1, size_t vstride, KP kp, VP vp, ACT act, FILL fill) {
;     ...
;   for (int kt = k0; kt <= k1; ++kt) {
;     const int kn = (kt < k1) ? kt + 1 : k1;
;     const int kn2 = (kt + 2 <= k1) ? kt + 2 : k1;
;     {
;       const bf16_t* v0 = vp(kn);
; #pragma unroll
;       for (int j = 0; j < 8; ++j) nxt.v[j] = *(const s16x4*)(v0 + 256 * j);
;     }
;     bf16x8 k2[4];
;     {
;       const bf16_t* krow = kp(kn2);
; #pragma unroll
;       for (int ss = 0; ss < 4; ++ss) k2[ss] = *(const bf16x8*)(krow + 512 * ss);
;     }
;     f32x16 s_next;
; #pragma unroll
;     for (int i = 0; i < 16; ++i) s_next[i] = 0.f;
; #pragma unroll
;     for (int ss = 0; ss < 4; ++ss) s_next = MFMA32(nxt.k[ss], qf[ss], s_next);
;     if (act(kt)) {
;       float lg[16];
;       fill(kt, s_cur, lg);
;       softmax_step_r(st, lg, cur);
;     }
;     s_cur = s_next;
; #pragma unroll
;     for (int i = 0; i < 8; ++i) cur.v[i] = nxt.v[i];
; #pragma unroll
;     for (int ss = 0; ss < 4; ++ss) nxt.k[ss] = k2[ss];
;   }
; }
.Lasel_skipb:
	s_xor_b32 s100, s100, 0x8000
	s_add_u32 s56, s56, 4
	s_cmp_le_u32 s56, s59
	s_cbranch_scc1 .Lasel_loop
	s_nop 15
	s_waitcnt vmcnt(0)
	s_mov_b64 s[58:59], 0
	s_branch .LBB0_701
